# SSD S3 tail (norm*gate writeback): 16 serialized load-wait-store round trips per unit replaced by all 32 loads in flight with counted vmcnt waits
# baseline (speedup 1.0000x reference)
; __device__ __forceinline__ unsigned pk2(float lo, float hi) { const f32x2 v = {lo, hi}; return __builtin_bit_cast(unsigned, __builtin_convertvector(v, bf16x2_t)); }
; __device__ __forceinline__ void ssd_s3_unit(LAS unsigned char* lds, int unit, const bf16_t* P0, const float* cw, const float* cb, const float* dt_bias, const float* a_log, const float* dskip, const float* norm_w,
;                                             const bf16_t* STATES, bf16_t* OMIX) {
;     ...
;     ss += __shfl_xor(ss, 16); ss += __shfl_xor(ss, 32);
;     const float rs = rsqrtf(ss * (1.f / 256.f) + 1e-6f);
;     asm volatile("s_waitcnt vmcnt(0)" ::: "memory");
; #pragma unroll 4
;     for (int q = 0; q < 16; ++q) { const int col = g * 256 + q * 16 + fq * 4; const f32x4 nw = *(const f32x4*)(norm_w + col);
;         u32x2* p = (u32x2*)(OMIX + row * D + 512 + col); const u32x2 v = *p;
;         u32x2 o; o.x = pk2(bflo(v.x) * rs * nw[0], bfhi(v.x) * rs * nw[1]); o.y = pk2(bflo(v.y) * rs * nw[2], bfhi(v.y) * rs * nw[3]); *p = o; }
.LBB0_972:
	ds_bpermute_b32 v0, v162, v183
	s_mov_b32 s56, 0x800000
	v_lshl_or_b32 v2, v125, 8, v107
	v_mov_b32_e32 v1, v109
	v_mov_b32_e32 v3, v109
	s_waitcnt lgkmcnt(0)
	v_add_f32_e32 v4, v183, v0
	ds_bpermute_b32 v5, v163, v4
	v_lshlrev_b32_e32 v0, 2, v2
	s_waitcnt vmcnt(0)
	v_lshlrev_b32_e32 v2, 1, v2
	v_lshl_add_u64 v[2:3], v[126:127], 0, v[2:3]
	s_waitcnt lgkmcnt(0)
	v_add_f32_e32 v4, v4, v5
	v_fmamk_f32 v4, v4, 0x3b800000, v171
	v_mul_f32_e32 v5, 0x4b800000, v4
	v_cmp_gt_f32_e32 vcc, s56, v4
	v_readlane_b32 s56, v254, 52
	v_readlane_b32 s57, v254, 53
	v_cndmask_b32_e32 v4, v4, v5, vcc
	v_rsq_f32_e32 v4, v4
	v_lshl_add_u64 v[0:1], s[56:57], 0, v[0:1]
	v_readlane_b32 s56, v254, 44
	v_readlane_b32 s57, v254, 45
	v_mul_f32_e32 v5, 0x45800000, v4
	v_cndmask_b32_e32 v4, v4, v5, vcc
	v_lshl_add_u64 v[2:3], s[56:57], 0, v[2:3]
	v_mov_b32_e32 v5, v4
	v_lshl_add_u64 v[6:7], v[2:3], 0, s[54:55]
	v_lshl_add_u64 v[8:9], v[6:7], 0, s[54:55]
	v_lshl_add_u64 v[10:11], v[8:9], 0, s[54:55]
	global_load_dwordx4 v[16:19], v[0:1], off
	global_load_dwordx2 v[80:81], v[2:3], off offset:-64
	global_load_dwordx4 v[20:23], v[0:1], off offset:64
	global_load_dwordx2 v[82:83], v[2:3], off offset:-32
	global_load_dwordx4 v[24:27], v[0:1], off offset:128
	global_load_dwordx2 v[84:85], v[2:3], off
	global_load_dwordx4 v[28:31], v[0:1], off offset:192
	global_load_dwordx2 v[86:87], v[2:3], off offset:32
	global_load_dwordx4 v[32:35], v[0:1], off offset:256
	global_load_dwordx2 v[88:89], v[6:7], off offset:-64
	global_load_dwordx4 v[36:39], v[0:1], off offset:320
	global_load_dwordx2 v[90:91], v[6:7], off offset:-32
	global_load_dwordx4 v[40:43], v[0:1], off offset:384
	global_load_dwordx2 v[92:93], v[6:7], off
	global_load_dwordx4 v[44:47], v[0:1], off offset:448
	global_load_dwordx2 v[186:187], v[6:7], off offset:32
	global_load_dwordx4 v[48:51], v[0:1], off offset:512
	global_load_dwordx2 v[188:189], v[8:9], off offset:-64
	global_load_dwordx4 v[52:55], v[0:1], off offset:576
	global_load_dwordx2 v[190:191], v[8:9], off offset:-32
	global_load_dwordx4 v[56:59], v[0:1], off offset:640
	global_load_dwordx2 v[192:193], v[8:9], off
	global_load_dwordx4 v[60:63], v[0:1], off offset:704
	global_load_dwordx2 v[194:195], v[8:9], off offset:32
	global_load_dwordx4 v[64:67], v[0:1], off offset:768
	global_load_dwordx2 v[196:197], v[10:11], off offset:-64
	global_load_dwordx4 v[68:71], v[0:1], off offset:832
	global_load_dwordx2 v[198:199], v[10:11], off offset:-32
	global_load_dwordx4 v[72:75], v[0:1], off offset:896
	global_load_dwordx2 v[202:203], v[10:11], off
	global_load_dwordx4 v[76:79], v[0:1], off offset:960
	global_load_dwordx2 v[204:205], v[10:11], off offset:32
	s_waitcnt vmcnt(30)
	v_lshlrev_b32_e32 v14, 16, v80
	v_and_b32_e32 v15, 0xffff0000, v80
	v_lshlrev_b32_e32 v12, 16, v81
	v_and_b32_e32 v13, 0xffff0000, v81
	v_pk_mul_f32 v[14:15], v[4:5], v[14:15]
	v_pk_mul_f32 v[12:13], v[4:5], v[12:13]
	v_pk_mul_f32 v[16:17], v[16:17], v[14:15]
	v_pk_mul_f32 v[18:19], v[18:19], v[12:13]
	v_cvt_pk_bf16_f32 v16, v16, v17
	v_cvt_pk_bf16_f32 v17, v18, v19
	global_store_dwordx2 v[2:3], v[16:17], off offset:-64
	s_waitcnt vmcnt(29)
	v_lshlrev_b32_e32 v14, 16, v82
	v_and_b32_e32 v15, 0xffff0000, v82
	v_lshlrev_b32_e32 v12, 16, v83
	v_and_b32_e32 v13, 0xffff0000, v83
	v_pk_mul_f32 v[14:15], v[4:5], v[14:15]
	v_pk_mul_f32 v[12:13], v[4:5], v[12:13]
	v_pk_mul_f32 v[20:21], v[20:21], v[14:15]
	v_pk_mul_f32 v[22:23], v[22:23], v[12:13]
	v_cvt_pk_bf16_f32 v20, v20, v21
	v_cvt_pk_bf16_f32 v21, v22, v23
	global_store_dwordx2 v[2:3], v[20:21], off offset:-32
	s_waitcnt vmcnt(28)
	v_lshlrev_b32_e32 v14, 16, v84
	v_and_b32_e32 v15, 0xffff0000, v84
	v_lshlrev_b32_e32 v12, 16, v85
	v_and_b32_e32 v13, 0xffff0000, v85
	v_pk_mul_f32 v[14:15], v[4:5], v[14:15]
	v_pk_mul_f32 v[12:13], v[4:5], v[12:13]
	v_pk_mul_f32 v[24:25], v[24:25], v[14:15]
	v_pk_mul_f32 v[26:27], v[26:27], v[12:13]
	v_cvt_pk_bf16_f32 v24, v24, v25
	v_cvt_pk_bf16_f32 v25, v26, v27
	global_store_dwordx2 v[2:3], v[24:25], off
	s_waitcnt vmcnt(27)
	v_lshlrev_b32_e32 v14, 16, v86
	v_and_b32_e32 v15, 0xffff0000, v86
	v_lshlrev_b32_e32 v12, 16, v87
	v_and_b32_e32 v13, 0xffff0000, v87
	v_pk_mul_f32 v[14:15], v[4:5], v[14:15]
	v_pk_mul_f32 v[12:13], v[4:5], v[12:13]
	v_pk_mul_f32 v[28:29], v[28:29], v[14:15]
	v_pk_mul_f32 v[30:31], v[30:31], v[12:13]
	v_cvt_pk_bf16_f32 v28, v28, v29
	v_cvt_pk_bf16_f32 v29, v30, v31
	global_store_dwordx2 v[2:3], v[28:29], off offset:32
	s_waitcnt vmcnt(26)
	v_lshlrev_b32_e32 v14, 16, v88
	v_and_b32_e32 v15, 0xffff0000, v88
	v_lshlrev_b32_e32 v12, 16, v89
	v_and_b32_e32 v13, 0xffff0000, v89
	v_pk_mul_f32 v[14:15], v[4:5], v[14:15]
	v_pk_mul_f32 v[12:13], v[4:5], v[12:13]
	v_pk_mul_f32 v[32:33], v[32:33], v[14:15]
	v_pk_mul_f32 v[34:35], v[34:35], v[12:13]
	v_cvt_pk_bf16_f32 v32, v32, v33
	v_cvt_pk_bf16_f32 v33, v34, v35
	global_store_dwordx2 v[6:7], v[32:33], off offset:-64
	s_waitcnt vmcnt(25)
; __device__ __forceinline__ unsigned pk2(float lo, float hi) { const f32x2 v = {lo, hi}; return __builtin_bit_cast(unsigned, __builtin_convertvector(v, bf16x2_t)); }
; #define INP(k) (*(const float* const volatile __attribute__((address_space(4)))*)(ka + 8 * (k)))
; __device__ __forceinline__ void ssd_s3_unit(LAS unsigned char* lds, int unit, const bf16_t* P0, const float* cw, const float* cb, const float* dt_bias, const float* a_log, const float* dskip, const float* norm_w,
;                                             const bf16_t* STATES, bf16_t* OMIX) {
;     ...
;     for (int q = 0; q < 16; ++q) { const int col = g * 256 + q * 16 + fq * 4; const f32x4 nw = *(const f32x4*)(norm_w + col);
;         u32x2* p = (u32x2*)(OMIX + row * D + 512 + col); const u32x2 v = *p;
;         u32x2 o; o.x = pk2(bflo(v.x) * rs * nw[0], bfhi(v.x) * rs * nw[1]); o.y = pk2(bflo(v.y) * rs * nw[2], bfhi(v.y) * rs * nw[3]); *p = o; }
; __global__ void __launch_bounds__(512, 2) mk_fwd(Args args) {
;     ...
;         for (int u = bx; u < 1024; u += G) ssd_s3_unit(lds, u, P, INP(16), INP(17), INP(18), INP(19), INP(20), INP(21), OMIX1, OMIX0);
	v_lshlrev_b32_e32 v14, 16, v90
	v_and_b32_e32 v15, 0xffff0000, v90
	v_lshlrev_b32_e32 v12, 16, v91
	v_and_b32_e32 v13, 0xffff0000, v91
	v_pk_mul_f32 v[14:15], v[4:5], v[14:15]
	v_pk_mul_f32 v[12:13], v[4:5], v[12:13]
	v_pk_mul_f32 v[36:37], v[36:37], v[14:15]
	v_pk_mul_f32 v[38:39], v[38:39], v[12:13]
	v_cvt_pk_bf16_f32 v36, v36, v37
	v_cvt_pk_bf16_f32 v37, v38, v39
	global_store_dwordx2 v[6:7], v[36:37], off offset:-32
	s_waitcnt vmcnt(24)
	v_lshlrev_b32_e32 v14, 16, v92
	v_and_b32_e32 v15, 0xffff0000, v92
	v_lshlrev_b32_e32 v12, 16, v93
	v_and_b32_e32 v13, 0xffff0000, v93
	v_pk_mul_f32 v[14:15], v[4:5], v[14:15]
	v_pk_mul_f32 v[12:13], v[4:5], v[12:13]
	v_pk_mul_f32 v[40:41], v[40:41], v[14:15]
	v_pk_mul_f32 v[42:43], v[42:43], v[12:13]
	v_cvt_pk_bf16_f32 v40, v40, v41
	v_cvt_pk_bf16_f32 v41, v42, v43
	global_store_dwordx2 v[6:7], v[40:41], off
	s_waitcnt vmcnt(23)
	v_lshlrev_b32_e32 v14, 16, v186
	v_and_b32_e32 v15, 0xffff0000, v186
	v_lshlrev_b32_e32 v12, 16, v187
	v_and_b32_e32 v13, 0xffff0000, v187
	v_pk_mul_f32 v[14:15], v[4:5], v[14:15]
	v_pk_mul_f32 v[12:13], v[4:5], v[12:13]
	v_pk_mul_f32 v[44:45], v[44:45], v[14:15]
	v_pk_mul_f32 v[46:47], v[46:47], v[12:13]
	v_cvt_pk_bf16_f32 v44, v44, v45
	v_cvt_pk_bf16_f32 v45, v46, v47
	global_store_dwordx2 v[6:7], v[44:45], off offset:32
	s_waitcnt vmcnt(22)
	v_lshlrev_b32_e32 v14, 16, v188
	v_and_b32_e32 v15, 0xffff0000, v188
	v_lshlrev_b32_e32 v12, 16, v189
	v_and_b32_e32 v13, 0xffff0000, v189
	v_pk_mul_f32 v[14:15], v[4:5], v[14:15]
	v_pk_mul_f32 v[12:13], v[4:5], v[12:13]
	v_pk_mul_f32 v[48:49], v[48:49], v[14:15]
	v_pk_mul_f32 v[50:51], v[50:51], v[12:13]
	v_cvt_pk_bf16_f32 v48, v48, v49
	v_cvt_pk_bf16_f32 v49, v50, v51
	global_store_dwordx2 v[8:9], v[48:49], off offset:-64
	s_waitcnt vmcnt(21)
	v_lshlrev_b32_e32 v14, 16, v190
	v_and_b32_e32 v15, 0xffff0000, v190
	v_lshlrev_b32_e32 v12, 16, v191
	v_and_b32_e32 v13, 0xffff0000, v191
	v_pk_mul_f32 v[14:15], v[4:5], v[14:15]
	v_pk_mul_f32 v[12:13], v[4:5], v[12:13]
	v_pk_mul_f32 v[52:53], v[52:53], v[14:15]
	v_pk_mul_f32 v[54:55], v[54:55], v[12:13]
	v_cvt_pk_bf16_f32 v52, v52, v53
	v_cvt_pk_bf16_f32 v53, v54, v55
	global_store_dwordx2 v[8:9], v[52:53], off offset:-32
	s_waitcnt vmcnt(20)
	v_lshlrev_b32_e32 v14, 16, v192
	v_and_b32_e32 v15, 0xffff0000, v192
	v_lshlrev_b32_e32 v12, 16, v193
	v_and_b32_e32 v13, 0xffff0000, v193
	v_pk_mul_f32 v[14:15], v[4:5], v[14:15]
	v_pk_mul_f32 v[12:13], v[4:5], v[12:13]
	v_pk_mul_f32 v[56:57], v[56:57], v[14:15]
	v_pk_mul_f32 v[58:59], v[58:59], v[12:13]
	v_cvt_pk_bf16_f32 v56, v56, v57
	v_cvt_pk_bf16_f32 v57, v58, v59
	global_store_dwordx2 v[8:9], v[56:57], off
	s_waitcnt vmcnt(19)
	v_lshlrev_b32_e32 v14, 16, v194
	v_and_b32_e32 v15, 0xffff0000, v194
	v_lshlrev_b32_e32 v12, 16, v195
	v_and_b32_e32 v13, 0xffff0000, v195
	v_pk_mul_f32 v[14:15], v[4:5], v[14:15]
	v_pk_mul_f32 v[12:13], v[4:5], v[12:13]
	v_pk_mul_f32 v[60:61], v[60:61], v[14:15]
	v_pk_mul_f32 v[62:63], v[62:63], v[12:13]
	v_cvt_pk_bf16_f32 v60, v60, v61
	v_cvt_pk_bf16_f32 v61, v62, v63
	global_store_dwordx2 v[8:9], v[60:61], off offset:32
	s_waitcnt vmcnt(18)
	v_lshlrev_b32_e32 v14, 16, v196
	v_and_b32_e32 v15, 0xffff0000, v196
	v_lshlrev_b32_e32 v12, 16, v197
	v_and_b32_e32 v13, 0xffff0000, v197
	v_pk_mul_f32 v[14:15], v[4:5], v[14:15]
	v_pk_mul_f32 v[12:13], v[4:5], v[12:13]
	v_pk_mul_f32 v[64:65], v[64:65], v[14:15]
	v_pk_mul_f32 v[66:67], v[66:67], v[12:13]
	v_cvt_pk_bf16_f32 v64, v64, v65
	v_cvt_pk_bf16_f32 v65, v66, v67
	global_store_dwordx2 v[10:11], v[64:65], off offset:-64
	s_waitcnt vmcnt(17)
	v_lshlrev_b32_e32 v14, 16, v198
	v_and_b32_e32 v15, 0xffff0000, v198
	v_lshlrev_b32_e32 v12, 16, v199
	v_and_b32_e32 v13, 0xffff0000, v199
	v_pk_mul_f32 v[14:15], v[4:5], v[14:15]
	v_pk_mul_f32 v[12:13], v[4:5], v[12:13]
	v_pk_mul_f32 v[68:69], v[68:69], v[14:15]
	v_pk_mul_f32 v[70:71], v[70:71], v[12:13]
	v_cvt_pk_bf16_f32 v68, v68, v69
	v_cvt_pk_bf16_f32 v69, v70, v71
	global_store_dwordx2 v[10:11], v[68:69], off offset:-32
	s_waitcnt vmcnt(16)
	v_lshlrev_b32_e32 v14, 16, v202
	v_and_b32_e32 v15, 0xffff0000, v202
	v_lshlrev_b32_e32 v12, 16, v203
	v_and_b32_e32 v13, 0xffff0000, v203
	v_pk_mul_f32 v[14:15], v[4:5], v[14:15]
	v_pk_mul_f32 v[12:13], v[4:5], v[12:13]
	v_pk_mul_f32 v[72:73], v[72:73], v[14:15]
	v_pk_mul_f32 v[74:75], v[74:75], v[12:13]
	v_cvt_pk_bf16_f32 v72, v72, v73
	v_cvt_pk_bf16_f32 v73, v74, v75
	global_store_dwordx2 v[10:11], v[72:73], off
	s_waitcnt vmcnt(15)
	v_lshlrev_b32_e32 v14, 16, v204
	v_and_b32_e32 v15, 0xffff0000, v204
	v_lshlrev_b32_e32 v12, 16, v205
	v_and_b32_e32 v13, 0xffff0000, v205
	v_pk_mul_f32 v[14:15], v[4:5], v[14:15]
	v_pk_mul_f32 v[12:13], v[4:5], v[12:13]
	v_pk_mul_f32 v[76:77], v[76:77], v[14:15]
	v_pk_mul_f32 v[78:79], v[78:79], v[12:13]
	v_cvt_pk_bf16_f32 v76, v76, v77
	v_cvt_pk_bf16_f32 v77, v78, v79
	global_store_dwordx2 v[10:11], v[76:77], off offset:32
	v_readlane_b32 s58, v253, 24
	v_readlane_b32 s59, v253, 25
	s_load_dwordx2 s[56:57], s[58:59], 0x130
	v_readlane_b32 s60, v254, 42
	v_readlane_b32 s61, v254, 43
	s_waitcnt lgkmcnt(0)
	s_add_i32 s33, s33, s56
	v_readlane_b32 s56, v254, 40
	v_readlane_b32 s57, v254, 41
	s_xor_b64 s[56:57], s[56:57], s[60:61]
	v_writelane_b32 v254, s56, 40
	s_cmpk_gt_i32 s33, 0x3ff
	s_nop 0
	v_writelane_b32 v254, s57, 41
	s_cbranch_scc0 .LBB0_792
